# sparse-attention top-k ranking loop rewritten: integer-key threshold compare (index tie-break folded into a per-lane threshold via an SGPR lane mask), 8 LDS reads in flight; 5 VALU per candidate step
# speedup vs baseline: 1.0112x; 1.0028x over previous
; DI void nsa_block(const P& p, int layer, int T, float* ldsf) {
;     ...
; #pragma unroll 1
;     for (int q = 0; q < 4; ++q) {
;       const int rr = wid * 4 + q;
;       const float v1 = I0[lane * 32 + rr], v2 = I0[(lane + 64) * 32 + rr];
;       int rank1 = 0, rank2 = 0;
; #pragma unroll 8
;       for (int jp = 0; jp < 128; ++jp) {
;         const float x = I0[jp * 32 + rr];
;         rank1 += ((x > v1) || (x == v1 && jp < lane)) ? 1 : 0;
;         rank2 += ((x > v2) || (x == v2 && jp < lane + 64)) ? 1 : 0;
;       }
;       const unsigned long long b1 = __ballot(rank1 < 16), b2 = __ballot(rank2 < 16);
;       if (lane == 0) {
;         selw[rr * 4 + 0] = (unsigned)b1; selw[rr * 4 + 1] = (unsigned)(b1 >> 32);
;         selw[rr * 4 + 2] = (unsigned)b2; selw[rr * 4 + 3] = (unsigned)(b2 >> 32);
;       }
.LBB0_151:
	v_add_u32_e32 v76, s23, v72
	v_lshlrev_b32_e32 v71, 2, v76
	v_add_u32_e32 v70, v75, v71
	v_add_u32_e32 v68, v74, v71
	ds_read_b32 v68, v68
	ds_read_b32 v70, v70
	v_add_u32_e32 v77, 0, v71
	s_waitcnt vmcnt(2)
	s_waitcnt lgkmcnt(0)
	v_mov_b32_e32 v71, v68
	v_mov_b32_e32 v73, v70
	v_add_u32_e32 v129, -1, v68
	v_add_u32_e32 v130, -1, v70
	v_mov_b32_e32 v78, 0
	v_mov_b32_e32 v79, 0
	v_mov_b32_e32 v80, 0
	v_mov_b32_e32 v81, 0
	v_mov_b32_e32 v131, v77
	s_mov_b64 s[10:11], -2
	s_mov_b32 s24, 0
.Lrank_p1:
	ds_read_b32 v120, v131
	ds_read_b32 v121, v131 offset:128
	ds_read_b32 v122, v131 offset:256
	ds_read_b32 v123, v131 offset:384
	ds_read_b32 v124, v131 offset:512
	ds_read_b32 v125, v131 offset:640
	ds_read_b32 v126, v131 offset:768
	ds_read_b32 v127, v131 offset:896
	v_add_u32_e32 v131, 0x400, v131
	s_waitcnt lgkmcnt(7)
	v_cndmask_b32_e64 v128, v68, v129, s[10:11]
	v_cmp_gt_i32_e64 s[12:13], v120, v128
	v_cmp_gt_i32_e64 s[14:15], v120, v130
	s_lshl_b64 s[10:11], s[10:11], 1
	s_nop 0
	v_addc_co_u32_e64 v78, s[0:1], 0, v78, s[12:13]
	v_addc_co_u32_e64 v80, s[0:1], 0, v80, s[14:15]
	s_waitcnt lgkmcnt(6)
	v_cndmask_b32_e64 v128, v68, v129, s[10:11]
	v_cmp_gt_i32_e64 s[12:13], v121, v128
	v_cmp_gt_i32_e64 s[14:15], v121, v130
	s_lshl_b64 s[10:11], s[10:11], 1
	s_nop 0
	v_addc_co_u32_e64 v78, s[0:1], 0, v78, s[12:13]
	v_addc_co_u32_e64 v80, s[0:1], 0, v80, s[14:15]
	s_waitcnt lgkmcnt(5)
	v_cndmask_b32_e64 v128, v68, v129, s[10:11]
	v_cmp_gt_i32_e64 s[12:13], v122, v128
	v_cmp_gt_i32_e64 s[14:15], v122, v130
	s_lshl_b64 s[10:11], s[10:11], 1
	s_nop 0
	v_addc_co_u32_e64 v78, s[0:1], 0, v78, s[12:13]
	v_addc_co_u32_e64 v80, s[0:1], 0, v80, s[14:15]
	s_waitcnt lgkmcnt(4)
	v_cndmask_b32_e64 v128, v68, v129, s[10:11]
	v_cmp_gt_i32_e64 s[12:13], v123, v128
	v_cmp_gt_i32_e64 s[14:15], v123, v130
	s_lshl_b64 s[10:11], s[10:11], 1
	s_nop 0
	v_addc_co_u32_e64 v78, s[0:1], 0, v78, s[12:13]
	v_addc_co_u32_e64 v80, s[0:1], 0, v80, s[14:15]
	s_waitcnt lgkmcnt(3)
	v_cndmask_b32_e64 v128, v68, v129, s[10:11]
	v_cmp_gt_i32_e64 s[12:13], v124, v128
	v_cmp_gt_i32_e64 s[14:15], v124, v130
	s_lshl_b64 s[10:11], s[10:11], 1
	s_nop 0
	v_addc_co_u32_e64 v78, s[0:1], 0, v78, s[12:13]
	v_addc_co_u32_e64 v80, s[0:1], 0, v80, s[14:15]
	s_waitcnt lgkmcnt(2)
	v_cndmask_b32_e64 v128, v68, v129, s[10:11]
	v_cmp_gt_i32_e64 s[12:13], v125, v128
	v_cmp_gt_i32_e64 s[14:15], v125, v130
	s_lshl_b64 s[10:11], s[10:11], 1
	s_nop 0
	v_addc_co_u32_e64 v78, s[0:1], 0, v78, s[12:13]
	v_addc_co_u32_e64 v80, s[0:1], 0, v80, s[14:15]
	s_waitcnt lgkmcnt(1)
	v_cndmask_b32_e64 v128, v68, v129, s[10:11]
	v_cmp_gt_i32_e64 s[12:13], v126, v128
	v_cmp_gt_i32_e64 s[14:15], v126, v130
	s_lshl_b64 s[10:11], s[10:11], 1
	s_nop 0
	v_addc_co_u32_e64 v78, s[0:1], 0, v78, s[12:13]
	v_addc_co_u32_e64 v80, s[0:1], 0, v80, s[14:15]
	s_waitcnt lgkmcnt(0)
	v_cndmask_b32_e64 v128, v68, v129, s[10:11]
	v_cmp_gt_i32_e64 s[12:13], v127, v128
	v_cmp_gt_i32_e64 s[14:15], v127, v130
	s_lshl_b64 s[10:11], s[10:11], 1
	s_nop 0
	v_addc_co_u32_e64 v78, s[0:1], 0, v78, s[12:13]
	v_addc_co_u32_e64 v80, s[0:1], 0, v80, s[14:15]
	s_add_i32 s24, s24, 8
	s_cmp_lt_u32 s24, 64
	s_cbranch_scc1 .Lrank_p1
	s_mov_b64 s[10:11], -2
	s_mov_b32 s24, 0
.Lrank_p2:
	ds_read_b32 v120, v131
	ds_read_b32 v121, v131 offset:128
	ds_read_b32 v122, v131 offset:256
	ds_read_b32 v123, v131 offset:384
	ds_read_b32 v124, v131 offset:512
	ds_read_b32 v125, v131 offset:640
	ds_read_b32 v126, v131 offset:768
	ds_read_b32 v127, v131 offset:896
	v_add_u32_e32 v131, 0x400, v131
	s_waitcnt lgkmcnt(7)
	v_cndmask_b32_e64 v128, v70, v130, s[10:11]
	v_cmp_gt_i32_e64 s[12:13], v120, v68
	v_cmp_gt_i32_e64 s[14:15], v120, v128
	s_lshl_b64 s[10:11], s[10:11], 1
	s_nop 0
	v_addc_co_u32_e64 v78, s[0:1], 0, v78, s[12:13]
	v_addc_co_u32_e64 v80, s[0:1], 0, v80, s[14:15]
	s_waitcnt lgkmcnt(6)
	v_cndmask_b32_e64 v128, v70, v130, s[10:11]
	v_cmp_gt_i32_e64 s[12:13], v121, v68
	v_cmp_gt_i32_e64 s[14:15], v121, v128
	s_lshl_b64 s[10:11], s[10:11], 1
	s_nop 0
	v_addc_co_u32_e64 v78, s[0:1], 0, v78, s[12:13]
	v_addc_co_u32_e64 v80, s[0:1], 0, v80, s[14:15]
	s_waitcnt lgkmcnt(5)
	v_cndmask_b32_e64 v128, v70, v130, s[10:11]
	v_cmp_gt_i32_e64 s[12:13], v122, v68
	v_cmp_gt_i32_e64 s[14:15], v122, v128
	s_lshl_b64 s[10:11], s[10:11], 1
	s_nop 0
	v_addc_co_u32_e64 v78, s[0:1], 0, v78, s[12:13]
	v_addc_co_u32_e64 v80, s[0:1], 0, v80, s[14:15]
	s_waitcnt lgkmcnt(4)
	v_cndmask_b32_e64 v128, v70, v130, s[10:11]
	v_cmp_gt_i32_e64 s[12:13], v123, v68
	v_cmp_gt_i32_e64 s[14:15], v123, v128
	s_lshl_b64 s[10:11], s[10:11], 1
	s_nop 0
	v_addc_co_u32_e64 v78, s[0:1], 0, v78, s[12:13]
	v_addc_co_u32_e64 v80, s[0:1], 0, v80, s[14:15]
	s_waitcnt lgkmcnt(3)
	v_cndmask_b32_e64 v128, v70, v130, s[10:11]
	v_cmp_gt_i32_e64 s[12:13], v124, v68
	v_cmp_gt_i32_e64 s[14:15], v124, v128
	s_lshl_b64 s[10:11], s[10:11], 1
	s_nop 0
	v_addc_co_u32_e64 v78, s[0:1], 0, v78, s[12:13]
	v_addc_co_u32_e64 v80, s[0:1], 0, v80, s[14:15]
	s_waitcnt lgkmcnt(2)
	v_cndmask_b32_e64 v128, v70, v130, s[10:11]
	v_cmp_gt_i32_e64 s[12:13], v125, v68
	v_cmp_gt_i32_e64 s[14:15], v125, v128
	s_lshl_b64 s[10:11], s[10:11], 1
	s_nop 0
	v_addc_co_u32_e64 v78, s[0:1], 0, v78, s[12:13]
	v_addc_co_u32_e64 v80, s[0:1], 0, v80, s[14:15]
	s_waitcnt lgkmcnt(1)
	v_cndmask_b32_e64 v128, v70, v130, s[10:11]
	v_cmp_gt_i32_e64 s[12:13], v126, v68
	v_cmp_gt_i32_e64 s[14:15], v126, v128
	s_lshl_b64 s[10:11], s[10:11], 1
	s_nop 0
	v_addc_co_u32_e64 v78, s[0:1], 0, v78, s[12:13]
	v_addc_co_u32_e64 v80, s[0:1], 0, v80, s[14:15]
	s_waitcnt lgkmcnt(0)
	v_cndmask_b32_e64 v128, v70, v130, s[10:11]
	v_cmp_gt_i32_e64 s[12:13], v127, v68
	v_cmp_gt_i32_e64 s[14:15], v127, v128
	s_lshl_b64 s[10:11], s[10:11], 1
	s_nop 0
	v_addc_co_u32_e64 v78, s[0:1], 0, v78, s[12:13]
	v_addc_co_u32_e64 v80, s[0:1], 0, v80, s[14:15]
	s_add_i32 s24, s24, 8
	s_cmp_lt_u32 s24, 64
	s_cbranch_scc1 .Lrank_p2
	v_add_u32_e32 v68, v81, v80
	v_add_u32_e32 v70, v78, v79
	v_cmp_gt_u32_e64 s[8:9], 16, v70
	v_cmp_gt_u32_e64 s[0:1], 16, v68
	s_and_saveexec_b64 s[2:3], vcc
	s_cbranch_execz .LBB0_150
	v_lshl_add_u32 v68, v76, 4, 0
	v_add_u32_e32 v68, 0x12000, v68
	v_mov_b32_e32 v76, s8
	v_mov_b32_e32 v77, s9
	v_mov_b32_e32 v78, s0
	v_mov_b32_e32 v79, s1
	ds_write_b128 v68, v[76:79]
	s_branch .LBB0_150
